# grid-barrier flag poll without s_sleep between polls
# baseline (speedup 1.0000x reference)
.Lxb1_spin:
	global_load_dword v3, v1, s[10:11] sc1
	s_waitcnt vmcnt(0)
	v_cmp_le_u32_e32 vcc, s73, v3
	s_cbranch_vccnz .Lxb1_acq
	s_branch .Lxb1_spin
